# attention P.V read addresses from a precomputed per-lane value (17 fewer VALU per wave-step) on top of the DMA address diet
# speedup vs baseline: 1.0027x; 1.0027x over previous
.LBB0_178:
	s_or_b64 exec, exec, s[6:7]
	s_waitcnt lgkmcnt(0)
	s_barrier
	v_mbcnt_lo_u32_b32 v2, -1, 0
	v_mbcnt_hi_u32_b32 v2, -1, v2
	s_load_dwordx2 s[6:7], s[0:1], 0x98
	s_waitcnt lgkmcnt(0)
	s_load_dwordx2 s[8:9], s[0:1], 16
	s_waitcnt lgkmcnt(0)
	s_load_dwordx2 s[10:11], s[0:1], 24
	s_waitcnt lgkmcnt(0)
	s_load_dwordx2 s[12:13], s[0:1], 32
	s_waitcnt lgkmcnt(0)
	s_load_dwordx2 s[14:15], s[0:1], 40
	s_waitcnt lgkmcnt(0)
	s_nop 0
	v_ashrrev_i32_e32 v3, 31, v2
	v_lshlrev_b64 v[4:5], 2, v[2:3]
	v_lshl_add_u64 v[6:7], s[8:9], 0, v[4:5]
	v_lshl_add_u64 v[8:9], s[10:11], 0, v[4:5]
	global_load_dword v10, v[6:7], off
	global_load_dword v11, v[6:7], off offset:256
	global_load_dword v12, v[8:9], off
	global_load_dword v13, v[8:9], off offset:256
	v_lshl_add_u64 v[6:7], s[12:13], 0, v[4:5]
	v_lshl_add_u64 v[4:5], s[14:15], 0, v[4:5]
	global_load_dword v8, v[6:7], off
	global_load_dword v9, v[6:7], off offset:256
	global_load_dword v14, v[4:5], off
	global_load_dword v15, v[4:5], off offset:256
	s_abs_i32 s13, s24
	v_cvt_f32_u32_e32 v3, s13
	v_lshlrev_b32_e32 v2, 2, v2
	v_xor_b32_e32 v6, 4, v2
	v_xor_b32_e32 v7, 8, v2
	v_xor_b32_e32 v16, 16, v2
	v_xor_b32_e32 v17, 32, v2
	v_xor_b32_e32 v18, 64, v2
	v_xor_b32_e32 v19, 0x80, v2
	v_rcp_iflag_f32_e32 v20, v3
	v_readfirstlane_b32 s10, v0
	s_lshr_b32 s10, s10, 4
	s_and_b32 s10, s10, 0xffffffc
	s_add_i32 s10, s10, 0
	s_mov_b32 s8, 0x3fb8aa3b
	s_add_i32 s29, s10, 0x20c00
	s_sub_i32 s15, 0, s13
	s_sub_i32 s11, s24, s17
	s_add_i32 s14, s11, 0x1ff
	s_sub_i32 s11, 0xfffffe01, s11
	s_xor_b32 s28, s14, s24
	s_max_i32 s14, s14, s11
	s_mov_b32 s9, 0xc2ce8ed0
	s_mov_b32 s12, 0x42b17218
	v_mov_b32_e32 v1, 0x7f800000
	s_ashr_i32 s28, s28, 31
	s_load_dwordx2 s[10:11], s[0:1], 48
	s_waitcnt lgkmcnt(0)
	s_mov_b32 s25, 0
	s_waitcnt vmcnt(4)
	v_pk_mul_f32 v[2:3], v[10:11], v[12:13]
	s_nop 0
	v_add_f32_e32 v2, v2, v3
	s_waitcnt vmcnt(0)
	v_pk_mul_f32 v[4:5], v[8:9], v[14:15]
	s_nop 0
	v_add_f32_e32 v3, v4, v5
	ds_bpermute_b32 v4, v6, v2
	ds_bpermute_b32 v5, v6, v3
	v_mul_f32_e32 v8, 0x4f7ffffe, v20
	v_cvt_u32_f32_e32 v8, v8
	v_mov_b32_e32 v6, s29
	s_waitcnt lgkmcnt(1)
	v_add_f32_e32 v2, v2, v4
	s_waitcnt lgkmcnt(0)
	v_add_f32_e32 v3, v3, v5
	ds_bpermute_b32 v4, v7, v2
	ds_bpermute_b32 v5, v7, v3
	v_readfirstlane_b32 s29, v8
	s_mul_i32 s15, s15, s29
	s_mul_hi_u32 s15, s29, s15
	s_waitcnt lgkmcnt(1)
	v_add_f32_e32 v2, v2, v4
	s_waitcnt lgkmcnt(0)
	v_add_f32_e32 v3, v3, v5
	ds_bpermute_b32 v4, v16, v2
	ds_bpermute_b32 v5, v16, v3
	s_add_i32 s29, s29, s15
	s_mul_hi_u32 s15, s14, s29
	s_mul_i32 s29, s15, s13
	s_waitcnt lgkmcnt(1)
	v_add_f32_e32 v2, v2, v4
	s_waitcnt lgkmcnt(0)
	v_add_f32_e32 v3, v3, v5
	ds_bpermute_b32 v4, v17, v2
	ds_bpermute_b32 v5, v17, v3
	s_sub_i32 s14, s14, s29
	s_add_i32 s30, s15, 1
	s_sub_i32 s29, s14, s13
	s_waitcnt lgkmcnt(1)
	v_add_f32_e32 v2, v2, v4
	s_waitcnt lgkmcnt(0)
	v_add_f32_e32 v3, v3, v5
	ds_bpermute_b32 v4, v18, v2
	ds_bpermute_b32 v5, v18, v3
	s_cmp_ge_u32 s14, s13
	s_cselect_b32 s15, s30, s15
	s_cselect_b32 s14, s29, s14
	s_waitcnt lgkmcnt(1)
	v_add_f32_e32 v2, v2, v4
	s_waitcnt lgkmcnt(0)
	v_add_f32_e32 v3, v3, v5
	ds_bpermute_b32 v4, v19, v2
	ds_bpermute_b32 v5, v19, v3
	s_add_i32 s29, s15, 1
	s_cmp_ge_u32 s14, s13
	s_cselect_b32 s13, s29, s15
	s_waitcnt lgkmcnt(1)
	v_add_f32_e32 v2, v2, v4
	s_waitcnt lgkmcnt(0)
	v_add_f32_e32 v3, v3, v5
	v_mul_f32_e32 v4, 0x3fb8aa3b, v2
	v_mul_f32_e32 v5, 0x3fb8aa3b, v3
	v_fma_f32 v7, v2, s8, -v4
	v_rndne_f32_e32 v8, v4
	v_fma_f32 v9, v3, s8, -v5
	v_rndne_f32_e32 v10, v5
	v_fmac_f32_e32 v7, 0x32a5705f, v2
	v_sub_f32_e32 v4, v4, v8
	v_fmac_f32_e32 v9, 0x32a5705f, v3
	v_sub_f32_e32 v5, v5, v10
	v_add_f32_e32 v4, v4, v7
	v_cvt_i32_f32_e32 v8, v8
	v_add_f32_e32 v5, v5, v9
	v_exp_f32_e32 v4, v4
	v_cvt_i32_f32_e32 v10, v10
	v_exp_f32_e32 v5, v5
	v_cmp_ngt_f32_e32 vcc, s9, v2
	v_ldexp_f32 v4, v4, v8
	s_xor_b32 s8, s13, s28
	v_ldexp_f32 v5, v5, v10
	v_cndmask_b32_e32 v4, 0, v4, vcc
	v_cmp_ngt_f32_e32 vcc, s9, v3
	s_sub_i32 s8, s8, s28
	s_cmp_lt_i32 s8, 1
	v_cndmask_b32_e32 v5, 0, v5, vcc
	v_cmp_nlt_f32_e32 vcc, s12, v2
	s_nop 1
	v_cndmask_b32_e32 v2, v1, v4, vcc
	v_cmp_nlt_f32_e32 vcc, s12, v3
	s_nop 1
	v_cndmask_b32_e32 v1, v1, v5, vcc
	v_sub_f32_e32 v1, v2, v1
	v_add_f32_e32 v1, 0x3e4ccccd, v1
	ds_write_b32 v6, v1
	s_waitcnt lgkmcnt(0)
	s_cbranch_scc1 .LBB0_463
	s_add_u32 s38, s6, 0x16100000
	s_addc_u32 s39, s7, 0
	s_add_u32 s40, s6, 0x3e100000
	s_addc_u32 s41, s7, 0
	s_lshl_b32 s8, s8, 1
	s_max_i32 s42, s8, 1
	s_add_u32 s43, s6, 0x16601100
	s_mov_b32 s14, 0xffd7ff00
	s_mov_b32 s28, 0xffd80000
	s_movk_i32 s30, 0xff00
	s_addc_u32 s44, s7, 0
	s_movk_i32 s45, 0x5000
	s_mov_b64 s[12:13], 0x100
	v_mov_b32_e32 v223, 0
	s_brev_b32 s46, -2
	s_add_i32 s47, 0, 0x18000
	s_mov_b32 s15, -1
	s_mov_b32 s29, -1
	s_movk_i32 s48, 0x70
	s_brev_b32 s49, 1
	s_mov_b32 s50, 0x41000000
	s_movk_i32 s51, 0x100
	s_mov_b32 s31, -1
	s_movk_i32 s52, 0xc000
	v_mov_b32_e32 v1, 0x3727c5ac
	s_mov_b32 s53, 0xf800000
	v_mov_b32_e32 v224, 0x260
	v_mov_b32_e32 v225, 0xff800000
	v_mbcnt_lo_u32_b32 v255, -1, 0
	v_mbcnt_hi_u32_b32 v255, -1, v255
	v_lshrrev_b32_e32 v251, 4, v255
	v_and_b32_e32 v252, 15, v255
	v_xor_b32_e32 v252, v252, v251
	v_lshlrev_b32_e32 v252, 4, v252
	v_mul_u32_u24_e32 v251, 0xa000, v251
	v_add_u32_e32 v251, v251, v252
	s_mul_i32 s98, s19, 0x50000
	v_add_u32_e32 v251, s98, v251
	v_xor_b32_e32 v252, 64, v251
	v_add_u32_e32 v252, 0x28000, v252
	v_bfe_u32 v253, v255, 2, 3
	s_and_b32 s98, s19, 1
	s_lshl_b32 s98, s98, 4
	v_or_b32_e32 v253, s98, v253
	v_mul_u32_u24_e32 v253, 0xa000, v253
	v_lshrrev_b32_e32 v254, 5, v255
	v_lshlrev_b32_e32 v254, 6, v254
	v_add_u32_e32 v253, v253, v254
	v_bfe_u32 v254, v255, 4, 1
	v_xor_b32_e32 v254, v254, v255
	v_and_b32_e32 v254, 3, v254
	v_lshlrev_b32_e32 v254, 4, v254
	v_add_u32_e32 v253, v253, v254
	v_xor_b32_e32 v254, 32, v253
	v_add_u32_e32 v254, 0x50000, v254
	v_lshrrev_b32_e32 v2, 3, v255
	v_ashrrev_i32_e32 v3, 5, v255
	v_and_or_b32 v2, v2, 2, v3
	v_lshlrev_b32_e32 v3, 1, v3
	v_bfe_u32 v5, v255, 1, 1
	v_and_b32_e32 v3, 2, v3
	v_and_b32_e32 v6, 12, v255
	v_or3_b32 v5, v6, v3, v5
	v_lshlrev_b32_e32 v2, 11, v2
	v_lshlrev_b32_e32 v7, 3, v255
	v_and_b32_e32 v7, 8, v7
	v_lshlrev_b32_e32 v5, 4, v5
	v_add3_u32 v255, v7, v2, v5
	s_branch .LBB0_182

.LBB0_184:
	v_add_f32_e32 v20, v189, v190
	v_fmac_f32_e32 v20, v187, v188
	v_add_f32_e32 v187, v18, v19
	v_fmac_f32_e32 v187, v20, v193
	s_add_i32 s89, s89, 2
	s_cmp_lg_u32 0, -1
	s_cselect_b32 s36, 0, 0
	s_add_i32 s36, s36, 0x18000
	s_waitcnt lgkmcnt(0)
	v_add_u32_e32 v220, s36, v255
	v_xor_b32_e32 v221, 0x110, v220
	ds_read_b64_tr_b16 v[18:19], v220 offset:0
	ds_read_b64_tr_b16 v[20:21], v221 offset:0
	v_xor_b32_e32 v222, 32, v220
	ds_read_b64_tr_b16 v[22:23], v222 offset:0
	v_xor_b32_e32 v226, 32, v221
	ds_read_b64_tr_b16 v[24:25], v226 offset:0
	ds_read_b64_tr_b16 v[26:27], v220 offset:0x200
	ds_read_b64_tr_b16 v[28:29], v221 offset:0x200
	s_waitcnt lgkmcnt(4)
	v_permlane16_swap_b32_e32 v10, v14
	v_permlane16_swap_b32_e32 v11, v15
	v_permlane16_swap_b32_e32 v12, v16
	v_permlane16_swap_b32_e32 v13, v17
	v_permlane16_swap_b32_e32 v2, v6
	v_permlane16_swap_b32_e32 v3, v7
	v_permlane16_swap_b32_e32 v4, v8
	v_permlane16_swap_b32_e32 v5, v9
	v_mfma_f32_16x16x32_bf16 v[30:33], v[10:13], v[18:21], v[74:77]
	v_mfma_f32_16x16x32_bf16 v[18:21], v[14:17], v[18:21], v[130:133]
	ds_read_b64_tr_b16 v[74:75], v222 offset:0x200
	ds_read_b64_tr_b16 v[76:77], v226 offset:0x200
	s_waitcnt lgkmcnt(4)
	v_mfma_f32_16x16x32_bf16 v[78:81], v[10:13], v[22:25], v[78:81]
	v_mfma_f32_16x16x32_bf16 v[22:25], v[14:17], v[22:25], v[134:137]
	ds_read_b64_tr_b16 v[130:131], v220 offset:0x400
	ds_read_b64_tr_b16 v[132:133], v221 offset:0x400
	s_waitcnt lgkmcnt(4)
	v_mfma_f32_16x16x32_bf16 v[82:85], v[10:13], v[26:29], v[82:85]
	v_mfma_f32_16x16x32_bf16 v[26:29], v[14:17], v[26:29], v[138:141]
	ds_read_b64_tr_b16 v[134:135], v222 offset:0x400
	ds_read_b64_tr_b16 v[136:137], v226 offset:0x400
	s_waitcnt lgkmcnt(4)
	v_mfma_f32_16x16x32_bf16 v[86:89], v[10:13], v[74:77], v[86:89]
	v_mfma_f32_16x16x32_bf16 v[74:77], v[14:17], v[74:77], v[142:145]
	ds_read_b64_tr_b16 v[138:139], v220 offset:0x600
	ds_read_b64_tr_b16 v[140:141], v221 offset:0x600
	s_waitcnt lgkmcnt(4)
	v_mfma_f32_16x16x32_bf16 v[90:93], v[10:13], v[130:133], v[90:93]
	v_mfma_f32_16x16x32_bf16 v[130:133], v[14:17], v[130:133], v[146:149]
	ds_read_b64_tr_b16 v[142:143], v222 offset:0x600
	ds_read_b64_tr_b16 v[144:145], v226 offset:0x600
	s_waitcnt lgkmcnt(4)
	v_mfma_f32_16x16x32_bf16 v[94:97], v[10:13], v[134:137], v[94:97]
	v_mfma_f32_16x16x32_bf16 v[134:137], v[14:17], v[134:137], v[150:153]
	ds_read_b64_tr_b16 v[146:147], v220 offset:0x2000
	ds_read_b64_tr_b16 v[148:149], v221 offset:0x2000
	s_waitcnt lgkmcnt(4)
	v_mfma_f32_16x16x32_bf16 v[98:101], v[10:13], v[138:141], v[98:101]
	v_mfma_f32_16x16x32_bf16 v[138:141], v[14:17], v[138:141], v[154:157]
	ds_read_b64_tr_b16 v[150:151], v222 offset:0x2000
	ds_read_b64_tr_b16 v[152:153], v226 offset:0x2000
	s_waitcnt lgkmcnt(4)
	v_mfma_f32_16x16x32_bf16 v[102:105], v[10:13], v[142:145], v[102:105]
	v_mfma_f32_16x16x32_bf16 v[158:161], v[14:17], v[142:145], v[158:161]
	ds_read_b64_tr_b16 v[142:143], v220 offset:0x2200
	ds_read_b64_tr_b16 v[144:145], v221 offset:0x2200
	s_waitcnt lgkmcnt(4)
	v_mfma_f32_16x16x32_bf16 v[106:109], v[10:13], v[146:149], v[106:109]
	v_mfma_f32_16x16x32_bf16 v[146:149], v[14:17], v[146:149], v[162:165]
	ds_read_b64_tr_b16 v[154:155], v222 offset:0x2200
	ds_read_b64_tr_b16 v[156:157], v226 offset:0x2200
	s_waitcnt lgkmcnt(4)
	v_mfma_f32_16x16x32_bf16 v[188:191], v[10:13], v[150:153], v[110:113]
	v_mfma_f32_16x16x32_bf16 v[192:195], v[14:17], v[150:153], v[166:169]
	ds_read_b64_tr_b16 v[110:111], v220 offset:0x2400
	ds_read_b64_tr_b16 v[112:113], v221 offset:0x2400
	s_waitcnt lgkmcnt(4)
	v_mfma_f32_16x16x32_bf16 v[114:117], v[10:13], v[142:145], v[114:117]
	v_mfma_f32_16x16x32_bf16 v[170:173], v[14:17], v[142:145], v[170:173]
	ds_read_b64_tr_b16 v[142:143], v222 offset:0x2400
	ds_read_b64_tr_b16 v[144:145], v226 offset:0x2400
	s_waitcnt lgkmcnt(4)
	v_mfma_f32_16x16x32_bf16 v[174:177], v[14:17], v[154:157], v[174:177]
	v_mfma_f32_16x16x32_bf16 v[196:199], v[10:13], v[154:157], v[118:121]
	ds_read_b64_tr_b16 v[118:119], v220 offset:0x2600
	ds_read_b64_tr_b16 v[120:121], v221 offset:0x2600
	s_waitcnt lgkmcnt(4)
	v_mfma_f32_16x16x32_bf16 v[200:203], v[10:13], v[110:113], v[122:125]
	v_mfma_f32_16x16x32_bf16 v[204:207], v[14:17], v[110:113], v[178:181]
	ds_read_b64_tr_b16 v[110:111], v222 offset:0x2600
	ds_read_b64_tr_b16 v[112:113], v226 offset:0x2600
	s_waitcnt lgkmcnt(4)
	v_mfma_f32_16x16x32_bf16 v[182:185], v[14:17], v[142:145], v[182:185]
	v_mfma_f32_16x16x32_bf16 v[208:211], v[10:13], v[142:145], v[126:129]
	ds_read_b64_tr_b16 v[122:123], v220 offset:0x4000
	ds_read_b64_tr_b16 v[124:125], v221 offset:0x4000
	s_waitcnt lgkmcnt(4)
	v_mfma_f32_16x16x32_bf16 v[212:215], v[10:13], v[118:121], v[66:69]
	v_mfma_f32_16x16x32_bf16 v[216:219], v[14:17], v[118:121], v[70:73]
	ds_read_b64_tr_b16 v[66:67], v222 offset:0x4000
	ds_read_b64_tr_b16 v[68:69], v226 offset:0x4000
	s_waitcnt lgkmcnt(4)
	v_mfma_f32_16x16x32_bf16 v[10:13], v[10:13], v[110:113], v[58:61]
	v_mfma_f32_16x16x32_bf16 v[14:17], v[14:17], v[110:113], v[62:65]
	ds_read_b64_tr_b16 v[70:71], v220 offset:0x4200
	ds_read_b64_tr_b16 v[72:73], v221 offset:0x4200
	s_waitcnt lgkmcnt(4)
	v_mfma_f32_16x16x32_bf16 v[58:61], v[2:5], v[122:125], v[30:33]
	v_mfma_f32_16x16x32_bf16 v[178:181], v[6:9], v[122:125], v[18:21]
	ds_read_b64_tr_b16 v[18:19], v222 offset:0x4200
	ds_read_b64_tr_b16 v[20:21], v226 offset:0x4200
	s_waitcnt lgkmcnt(4)
	v_mfma_f32_16x16x32_bf16 v[62:65], v[2:5], v[66:69], v[78:81]
	v_mfma_f32_16x16x32_bf16 v[166:169], v[6:9], v[66:69], v[22:25]
	ds_read_b64_tr_b16 v[22:23], v220 offset:0x4400
	ds_read_b64_tr_b16 v[24:25], v221 offset:0x4400
	s_waitcnt lgkmcnt(4)
	v_mfma_f32_16x16x32_bf16 v[66:69], v[2:5], v[70:73], v[82:85]
	v_mfma_f32_16x16x32_bf16 v[162:165], v[6:9], v[70:73], v[26:29]
	ds_read_b64_tr_b16 v[26:27], v222 offset:0x4400
	ds_read_b64_tr_b16 v[28:29], v226 offset:0x4400
	s_waitcnt lgkmcnt(4)
	v_mfma_f32_16x16x32_bf16 v[70:73], v[2:5], v[18:21], v[86:89]
	v_mfma_f32_16x16x32_bf16 v[154:157], v[6:9], v[18:21], v[74:77]
	ds_read_b64_tr_b16 v[18:19], v220 offset:0x4600
	ds_read_b64_tr_b16 v[20:21], v221 offset:0x4600
	s_waitcnt lgkmcnt(4)
	v_mfma_f32_16x16x32_bf16 v[74:77], v[2:5], v[22:25], v[90:93]
	v_mfma_f32_16x16x32_bf16 v[150:153], v[6:9], v[22:25], v[130:133]
	ds_read_b64_tr_b16 v[22:23], v222 offset:0x4600
	ds_read_b64_tr_b16 v[24:25], v226 offset:0x4600
	s_waitcnt lgkmcnt(4)
	v_mfma_f32_16x16x32_bf16 v[82:85], v[2:5], v[26:29], v[94:97]
	v_mfma_f32_16x16x32_bf16 v[142:145], v[6:9], v[26:29], v[134:137]
	ds_read_b64_tr_b16 v[26:27], v220 offset:0x6000
	ds_read_b64_tr_b16 v[28:29], v221 offset:0x6000
	s_waitcnt lgkmcnt(4)
	v_mfma_f32_16x16x32_bf16 v[90:93], v[2:5], v[18:21], v[98:101]
	v_mfma_f32_16x16x32_bf16 v[138:141], v[6:9], v[18:21], v[138:141]
	ds_read_b64_tr_b16 v[18:19], v222 offset:0x6000
	ds_read_b64_tr_b16 v[20:21], v226 offset:0x6000
	s_waitcnt lgkmcnt(4)
	v_mfma_f32_16x16x32_bf16 v[98:101], v[2:5], v[22:25], v[102:105]
	v_mfma_f32_16x16x32_bf16 v[130:133], v[6:9], v[22:25], v[158:161]
	ds_read_b64_tr_b16 v[22:23], v220 offset:0x6200
	ds_read_b64_tr_b16 v[24:25], v221 offset:0x6200
	s_waitcnt lgkmcnt(4)
	v_mfma_f32_16x16x32_bf16 v[110:113], v[2:5], v[26:29], v[106:109]
	v_mfma_f32_16x16x32_bf16 v[126:129], v[6:9], v[26:29], v[146:149]
	ds_read_b64_tr_b16 v[26:27], v222 offset:0x6200
	ds_read_b64_tr_b16 v[28:29], v226 offset:0x6200
	s_waitcnt lgkmcnt(4)
	v_mfma_f32_16x16x32_bf16 v[122:125], v[2:5], v[18:21], v[188:191]
	v_mfma_f32_16x16x32_bf16 v[118:121], v[6:9], v[18:21], v[192:195]
	ds_read_b64_tr_b16 v[18:19], v220 offset:0x6400
	ds_read_b64_tr_b16 v[20:21], v221 offset:0x6400
	s_waitcnt lgkmcnt(4)
	v_mfma_f32_16x16x32_bf16 v[134:137], v[2:5], v[22:25], v[114:117]
	v_mfma_f32_16x16x32_bf16 v[114:117], v[6:9], v[22:25], v[170:173]
	ds_read_b64_tr_b16 v[22:23], v222 offset:0x6400
	ds_read_b64_tr_b16 v[24:25], v226 offset:0x6400
	s_waitcnt lgkmcnt(4)
	v_mfma_f32_16x16x32_bf16 v[146:149], v[2:5], v[26:29], v[196:199]
	v_mfma_f32_16x16x32_bf16 v[106:109], v[6:9], v[26:29], v[174:177]
	ds_read_b64_tr_b16 v[26:27], v220 offset:0x6600
	ds_read_b64_tr_b16 v[28:29], v221 offset:0x6600
	s_waitcnt lgkmcnt(4)
	v_mfma_f32_16x16x32_bf16 v[158:161], v[2:5], v[18:21], v[200:203]
	v_mfma_f32_16x16x32_bf16 v[102:105], v[6:9], v[18:21], v[204:207]
	ds_read_b64_tr_b16 v[18:19], v222 offset:0x6600
	ds_read_b64_tr_b16 v[20:21], v226 offset:0x6600
	s_waitcnt lgkmcnt(4)
	v_mfma_f32_16x16x32_bf16 v[174:177], v[2:5], v[22:25], v[208:211]
	v_mfma_f32_16x16x32_bf16 v[94:97], v[6:9], v[22:25], v[182:185]
	s_waitcnt lgkmcnt(2)
	v_mfma_f32_16x16x32_bf16 v[182:185], v[2:5], v[26:29], v[212:215]
	v_mfma_f32_16x16x32_bf16 v[86:89], v[6:9], v[26:29], v[216:219]
	s_waitcnt lgkmcnt(0)
	v_mfma_f32_16x16x32_bf16 v[170:173], v[2:5], v[18:21], v[10:13]
	v_mfma_f32_16x16x32_bf16 v[78:81], v[6:9], v[18:21], v[14:17]
	s_addk_i32 s86, 0xff80
	s_addk_i32 s79, 0x80
	s_add_u32 s8, s8, 0x500000
	s_addc_u32 s9, s9, 0
	s_and_b64 vcc, exec, s[34:35]
	s_cbranch_vccnz .LBB0_202

.LBB0_192:
	s_cmp_lg_u32 0, -1
	s_cselect_b32 s34, 0, 0
	s_add_i32 s34, s34, 0x8000
	s_waitcnt lgkmcnt(0)
	v_add_u32_e32 v220, s34, v255
	v_xor_b32_e32 v221, 0x110, v220
	ds_read_b64_tr_b16 v[18:19], v220 offset:0
	ds_read_b64_tr_b16 v[20:21], v221 offset:0
	v_xor_b32_e32 v222, 32, v220
	ds_read_b64_tr_b16 v[22:23], v222 offset:0
	v_xor_b32_e32 v250, 32, v221
	ds_read_b64_tr_b16 v[24:25], v250 offset:0
	ds_read_b64_tr_b16 v[26:27], v220 offset:0x200
	ds_read_b64_tr_b16 v[28:29], v221 offset:0x200
	s_waitcnt lgkmcnt(4)
	v_permlane16_swap_b32_e32 v10, v14
	v_permlane16_swap_b32_e32 v11, v15
	v_permlane16_swap_b32_e32 v12, v16
	v_permlane16_swap_b32_e32 v13, v17
	v_permlane16_swap_b32_e32 v2, v6
	v_permlane16_swap_b32_e32 v3, v7
	v_permlane16_swap_b32_e32 v4, v8
	v_permlane16_swap_b32_e32 v5, v9
	v_mfma_f32_16x16x32_bf16 v[30:33], v[10:13], v[18:21], v[58:61]
	v_mfma_f32_16x16x32_bf16 v[18:21], v[14:17], v[18:21], v[178:181]
	ds_read_b64_tr_b16 v[58:59], v222 offset:0x200
	ds_read_b64_tr_b16 v[60:61], v250 offset:0x200
	s_waitcnt lgkmcnt(4)
	v_mfma_f32_16x16x32_bf16 v[62:65], v[10:13], v[22:25], v[62:65]
	v_mfma_f32_16x16x32_bf16 v[22:25], v[14:17], v[22:25], v[166:169]
	ds_read_b64_tr_b16 v[166:167], v220 offset:0x400
	ds_read_b64_tr_b16 v[168:169], v221 offset:0x400
	s_waitcnt lgkmcnt(4)
	v_mfma_f32_16x16x32_bf16 v[66:69], v[10:13], v[26:29], v[66:69]
	v_mfma_f32_16x16x32_bf16 v[26:29], v[14:17], v[26:29], v[162:165]
	ds_read_b64_tr_b16 v[162:163], v222 offset:0x400
	ds_read_b64_tr_b16 v[164:165], v250 offset:0x400
	s_waitcnt lgkmcnt(4)
	v_mfma_f32_16x16x32_bf16 v[70:73], v[10:13], v[58:61], v[70:73]
	v_mfma_f32_16x16x32_bf16 v[58:61], v[14:17], v[58:61], v[154:157]
	ds_read_b64_tr_b16 v[154:155], v220 offset:0x600
	ds_read_b64_tr_b16 v[156:157], v221 offset:0x600
	s_waitcnt lgkmcnt(4)
	v_mfma_f32_16x16x32_bf16 v[178:181], v[10:13], v[166:169], v[74:77]
	v_mfma_f32_16x16x32_bf16 v[150:153], v[14:17], v[166:169], v[150:153]
	ds_read_b64_tr_b16 v[74:75], v222 offset:0x600
	ds_read_b64_tr_b16 v[76:77], v250 offset:0x600
	s_waitcnt lgkmcnt(4)
	v_mfma_f32_16x16x32_bf16 v[166:169], v[10:13], v[162:165], v[82:85]
	v_mfma_f32_16x16x32_bf16 v[162:165], v[14:17], v[162:165], v[142:145]
	ds_read_b64_tr_b16 v[82:83], v220 offset:0x2000
	ds_read_b64_tr_b16 v[84:85], v221 offset:0x2000
	s_waitcnt lgkmcnt(4)
	v_mfma_f32_16x16x32_bf16 v[192:195], v[10:13], v[154:157], v[90:93]
	v_mfma_f32_16x16x32_bf16 v[154:157], v[14:17], v[154:157], v[138:141]
	ds_read_b64_tr_b16 v[90:91], v222 offset:0x2000
	ds_read_b64_tr_b16 v[92:93], v250 offset:0x2000
	s_waitcnt lgkmcnt(4)
	v_mfma_f32_16x16x32_bf16 v[196:199], v[10:13], v[74:77], v[98:101]
	v_mfma_f32_16x16x32_bf16 v[200:203], v[14:17], v[74:77], v[130:133]
	ds_read_b64_tr_b16 v[74:75], v220 offset:0x2200
	ds_read_b64_tr_b16 v[76:77], v221 offset:0x2200
	s_waitcnt lgkmcnt(4)
	v_mfma_f32_16x16x32_bf16 v[110:113], v[10:13], v[82:85], v[110:113]
	v_mfma_f32_16x16x32_bf16 v[126:129], v[14:17], v[82:85], v[126:129]
	ds_read_b64_tr_b16 v[82:83], v222 offset:0x2200
	ds_read_b64_tr_b16 v[84:85], v250 offset:0x2200
	s_waitcnt lgkmcnt(4)
	v_mfma_f32_16x16x32_bf16 v[122:125], v[10:13], v[90:93], v[122:125]
	v_mfma_f32_16x16x32_bf16 v[118:121], v[14:17], v[90:93], v[118:121]
	ds_read_b64_tr_b16 v[90:91], v220 offset:0x2400
	ds_read_b64_tr_b16 v[92:93], v221 offset:0x2400
	s_waitcnt lgkmcnt(4)
	v_mfma_f32_16x16x32_bf16 v[204:207], v[10:13], v[74:77], v[134:137]
	v_mfma_f32_16x16x32_bf16 v[208:211], v[14:17], v[74:77], v[114:117]
	ds_read_b64_tr_b16 v[74:75], v222 offset:0x2400
	ds_read_b64_tr_b16 v[76:77], v250 offset:0x2400
	s_waitcnt lgkmcnt(4)
	v_mfma_f32_16x16x32_bf16 v[212:215], v[10:13], v[82:85], v[146:149]
	v_mfma_f32_16x16x32_bf16 v[216:219], v[14:17], v[82:85], v[106:109]
	ds_read_b64_tr_b16 v[82:83], v220 offset:0x2600
	ds_read_b64_tr_b16 v[84:85], v221 offset:0x2600
	s_waitcnt lgkmcnt(4)
	v_mfma_f32_16x16x32_bf16 v[226:229], v[10:13], v[90:93], v[158:161]
	v_mfma_f32_16x16x32_bf16 v[230:233], v[14:17], v[90:93], v[102:105]
	ds_read_b64_tr_b16 v[90:91], v222 offset:0x2600
	ds_read_b64_tr_b16 v[92:93], v250 offset:0x2600
	s_waitcnt lgkmcnt(4)
	v_mfma_f32_16x16x32_bf16 v[234:237], v[10:13], v[74:77], v[174:177]
	v_mfma_f32_16x16x32_bf16 v[238:241], v[14:17], v[74:77], v[94:97]
	ds_read_b64_tr_b16 v[94:95], v220 offset:0x4000
	ds_read_b64_tr_b16 v[96:97], v221 offset:0x4000
	s_waitcnt lgkmcnt(4)
	v_mfma_f32_16x16x32_bf16 v[242:245], v[10:13], v[82:85], v[182:185]
	v_mfma_f32_16x16x32_bf16 v[246:249], v[14:17], v[82:85], v[86:89]
	ds_read_b64_tr_b16 v[82:83], v222 offset:0x4000
	ds_read_b64_tr_b16 v[84:85], v250 offset:0x4000
	s_waitcnt lgkmcnt(4)
	v_mfma_f32_16x16x32_bf16 v[10:13], v[10:13], v[90:93], v[170:173]
	v_mfma_f32_16x16x32_bf16 v[14:17], v[14:17], v[90:93], v[78:81]
	ds_read_b64_tr_b16 v[86:87], v220 offset:0x4200
	ds_read_b64_tr_b16 v[88:89], v221 offset:0x4200
	s_waitcnt lgkmcnt(4)
	v_mfma_f32_16x16x32_bf16 v[74:77], v[2:5], v[94:97], v[30:33]
	v_mfma_f32_16x16x32_bf16 v[130:133], v[6:9], v[94:97], v[18:21]
	ds_read_b64_tr_b16 v[18:19], v222 offset:0x4200
	ds_read_b64_tr_b16 v[20:21], v250 offset:0x4200
	s_waitcnt lgkmcnt(4)
	v_mfma_f32_16x16x32_bf16 v[78:81], v[2:5], v[82:85], v[62:65]
	v_mfma_f32_16x16x32_bf16 v[134:137], v[6:9], v[82:85], v[22:25]
	ds_read_b64_tr_b16 v[22:23], v220 offset:0x4400
	ds_read_b64_tr_b16 v[24:25], v221 offset:0x4400
	s_waitcnt lgkmcnt(4)
	v_mfma_f32_16x16x32_bf16 v[82:85], v[2:5], v[86:89], v[66:69]
	v_mfma_f32_16x16x32_bf16 v[138:141], v[6:9], v[86:89], v[26:29]
	ds_read_b64_tr_b16 v[26:27], v222 offset:0x4400
	ds_read_b64_tr_b16 v[28:29], v250 offset:0x4400
	s_waitcnt lgkmcnt(4)
	v_mfma_f32_16x16x32_bf16 v[86:89], v[2:5], v[18:21], v[70:73]
	v_mfma_f32_16x16x32_bf16 v[142:145], v[6:9], v[18:21], v[58:61]
	ds_read_b64_tr_b16 v[18:19], v220 offset:0x4600
	ds_read_b64_tr_b16 v[20:21], v221 offset:0x4600
	s_waitcnt lgkmcnt(4)
	v_mfma_f32_16x16x32_bf16 v[90:93], v[2:5], v[22:25], v[178:181]
	v_mfma_f32_16x16x32_bf16 v[146:149], v[6:9], v[22:25], v[150:153]
	ds_read_b64_tr_b16 v[22:23], v222 offset:0x4600
	ds_read_b64_tr_b16 v[24:25], v250 offset:0x4600
	s_waitcnt lgkmcnt(4)
	v_mfma_f32_16x16x32_bf16 v[94:97], v[2:5], v[26:29], v[166:169]
	v_mfma_f32_16x16x32_bf16 v[150:153], v[6:9], v[26:29], v[162:165]
	ds_read_b64_tr_b16 v[26:27], v220 offset:0x6000
	ds_read_b64_tr_b16 v[28:29], v221 offset:0x6000
	s_waitcnt lgkmcnt(4)
	v_mfma_f32_16x16x32_bf16 v[98:101], v[2:5], v[18:21], v[192:195]
	v_mfma_f32_16x16x32_bf16 v[154:157], v[6:9], v[18:21], v[154:157]
	ds_read_b64_tr_b16 v[18:19], v222 offset:0x6000
	ds_read_b64_tr_b16 v[20:21], v250 offset:0x6000
	s_waitcnt lgkmcnt(4)
	v_mfma_f32_16x16x32_bf16 v[102:105], v[2:5], v[22:25], v[196:199]
	v_mfma_f32_16x16x32_bf16 v[158:161], v[6:9], v[22:25], v[200:203]
	ds_read_b64_tr_b16 v[22:23], v220 offset:0x6200
	ds_read_b64_tr_b16 v[24:25], v221 offset:0x6200
	s_waitcnt lgkmcnt(4)
	v_mfma_f32_16x16x32_bf16 v[106:109], v[2:5], v[26:29], v[110:113]
	v_mfma_f32_16x16x32_bf16 v[162:165], v[6:9], v[26:29], v[126:129]
	ds_read_b64_tr_b16 v[26:27], v222 offset:0x6200
	ds_read_b64_tr_b16 v[28:29], v250 offset:0x6200
	s_waitcnt lgkmcnt(4)
	v_mfma_f32_16x16x32_bf16 v[110:113], v[2:5], v[18:21], v[122:125]
	v_mfma_f32_16x16x32_bf16 v[166:169], v[6:9], v[18:21], v[118:121]
	ds_read_b64_tr_b16 v[18:19], v220 offset:0x6400
	ds_read_b64_tr_b16 v[20:21], v221 offset:0x6400
	s_waitcnt lgkmcnt(4)
	v_mfma_f32_16x16x32_bf16 v[114:117], v[2:5], v[22:25], v[204:207]
	v_mfma_f32_16x16x32_bf16 v[170:173], v[6:9], v[22:25], v[208:211]
	ds_read_b64_tr_b16 v[22:23], v222 offset:0x6400
	ds_read_b64_tr_b16 v[24:25], v250 offset:0x6400
	s_waitcnt lgkmcnt(4)
	v_mfma_f32_16x16x32_bf16 v[118:121], v[2:5], v[26:29], v[212:215]
	v_mfma_f32_16x16x32_bf16 v[174:177], v[6:9], v[26:29], v[216:219]
	ds_read_b64_tr_b16 v[26:27], v220 offset:0x6600
	ds_read_b64_tr_b16 v[28:29], v221 offset:0x6600
	s_waitcnt lgkmcnt(4)
	v_mfma_f32_16x16x32_bf16 v[122:125], v[2:5], v[18:21], v[226:229]
	v_mfma_f32_16x16x32_bf16 v[178:181], v[6:9], v[18:21], v[230:233]
	ds_read_b64_tr_b16 v[18:19], v222 offset:0x6600
	ds_read_b64_tr_b16 v[20:21], v250 offset:0x6600
	s_waitcnt lgkmcnt(4)
	v_mfma_f32_16x16x32_bf16 v[126:129], v[2:5], v[22:25], v[234:237]
	v_mfma_f32_16x16x32_bf16 v[182:185], v[6:9], v[22:25], v[238:241]
	s_waitcnt lgkmcnt(2)
	v_mfma_f32_16x16x32_bf16 v[66:69], v[2:5], v[26:29], v[242:245]
	v_mfma_f32_16x16x32_bf16 v[70:73], v[6:9], v[26:29], v[246:249]
	s_waitcnt lgkmcnt(0)
	v_mfma_f32_16x16x32_bf16 v[58:61], v[2:5], v[18:21], v[10:13]
	v_mfma_f32_16x16x32_bf16 v[62:65], v[6:9], v[18:21], v[14:17]
	s_cmp_ge_u32 s89, s80
	s_waitcnt vmcnt(0)
	s_barrier
	s_cselect_b64 s[34:35], -1, 0
	s_and_b64 vcc, exec, s[34:35]
	v_mbcnt_lo_u32_b32 v192, -1, 0
	v_mbcnt_hi_u32_b32 v192, -1, v192
	s_cbranch_vccnz .LBB0_194
	s_add_u32 s98, s8, s30
	s_addc_u32 s99, s9, s31
	s_mov_b32 m0, s62
	s_addk_i32 s36, 0x80
	global_load_lds_dwordx4 v251, s[98:99]
	s_mov_b32 m0, s63
	s_mul_hi_i32 s37, s36, 0xa000
	global_load_lds_dwordx4 v251, s[8:9]
	s_mov_b32 m0, s66
	s_mul_i32 s36, s36, 0xa000
	global_load_lds_dwordx4 v252, s[98:99]
	s_mov_b32 m0, s67
	s_add_u32 s36, s82, s36
	global_load_lds_dwordx4 v252, s[8:9]
	s_addc_u32 s37, s83, s37
	s_add_u32 s98, s36, 0x80
	s_addc_u32 s99, s37, 0
	s_mov_b32 m0, s71
	s_nop 0
	global_load_lds_dwordx4 v253, s[36:37]
	s_mov_b32 m0, s72
	s_nop 0
	global_load_lds_dwordx4 v253, s[98:99]
	s_mov_b32 m0, s75
	s_nop 0
	global_load_lds_dwordx4 v254, s[36:37]
	s_mov_b32 m0, s78
	s_nop 0
	global_load_lds_dwordx4 v254, s[98:99]
